# P5 out stores with nt (streaming) hint, on cp3
# baseline (speedup 1.0000x reference)
;     __device__ __forceinline__ void operator()(const f32x4 (&acc)[2][2][4][2], const Unit& u, int wr, int wc, int fr, int fq) const {
;         const size_t row0 = (size_t)u.pm * BM + wr * 64 + fr; const int col0 = u.pn * BM + wc * 32 + 4 * fq; const float* gp = gate + (size_t)(u.pm >> 4) * 3072 + col0;
;         f32x4 gv[2][2];
; #pragma unroll
;         for (int bj = 0; bj < 2; ++bj)
; #pragma unroll
;             for (int n = 0; n < 2; ++n) gv[bj][n] = *(const f32x4*)(gp + bj * HALF + n * 16);
; #pragma unroll
;         for (int ai = 0; ai < 2; ++ai) {
;             f32x4 xv[4][2][2];
; #pragma unroll
;             for (int m = 0; m < 4; ++m) { const size_t off = (row0 + ai * HALF + m * 16) * 1024 + col0;
; #pragma unroll
;                 for (int bj = 0; bj < 2; ++bj)
; #pragma unroll
;                     for (int n = 0; n < 2; ++n) xv[m][bj][n] = *(const f32x4*)(x + off + bj * HALF + n * 16); }
;             asm volatile("" ::: "memory");
; #pragma unroll
;             for (int m = 0; m < 4; ++m) { const size_t off = (row0 + ai * HALF + m * 16) * 1024 + col0;
; #pragma unroll
;                 for (int bj = 0; bj < 2; ++bj)
; #pragma unroll
;                     for (int n = 0; n < 2; ++n) *(f32x4*)(out + off + bj * HALF + n * 16) = xv[m][bj][n] + gv[bj][n] * acc[ai][bj][m][n]; }
;             asm volatile("" ::: "memory"); }
.LBB0_588:
	s_ashr_i32 s23, s30, 4
	s_ashr_i32 s31, s30, 31
	v_lshl_or_b32 v128, s61, 8, v163
	s_mul_hi_i32 s25, s23, 0x3000
	s_mulk_i32 s23, 0x3000
	s_add_u32 s34, s50, s23
	v_ashrrev_i32_e32 v129, 31, v128
	s_addc_u32 s35, s51, s25
	v_lshlrev_b64 v[232:233], 2, v[128:129]
	v_mbcnt_lo_u32_b32 v246, -1, 0
	v_mbcnt_hi_u32_b32 v246, -1, v246
	v_bfe_u32 v246, v246, 3, 1
	v_mul_i32_i24_e32 v246, 0xffff8040, v246
	v_ashrrev_i32_e32 v247, 31, v246
	v_lshl_add_u64 v[246:247], v[232:233], 0, v[246:247]
	v_mov_b32_e32 v248, 0x8000
	v_mov_b32_e32 v249, 0
	s_lshl_b64 s[30:31], s[30:31], 20
	v_lshl_add_u64 v[158:159], s[4:5], 0, v[232:233]
	v_lshl_add_u64 v[234:235], s[30:31], 0, v[148:149]
	v_lshl_add_u64 v[128:129], s[34:35], 0, v[232:233]
	v_lshl_add_u64 v[160:161], v[158:159], 0, v[234:235]
	global_load_dwordx4 v[168:171], v[160:161], off
	global_load_dwordx4 v[140:143], v[128:129], off
	global_load_dwordx4 v[136:139], v[128:129], off offset:64
	global_load_dwordx4 v[172:175], v[160:161], off offset:64
	global_load_dwordx4 v[176:179], v[160:161], off offset:512
	global_load_dwordx4 v[132:135], v[128:129], off offset:512
	s_nop 0
	global_load_dwordx4 v[128:131], v[128:129], off offset:576
	s_nop 0
	global_load_dwordx4 v[180:183], v[160:161], off offset:576
	v_or_b32_e32 v236, 0x10000, v234
	v_mov_b32_e32 v237, v235
	v_or_b32_e32 v238, 0x20000, v234
	v_mov_b32_e32 v239, v235
	v_or_b32_e32 v240, 0x30000, v234
	v_mov_b32_e32 v241, v235
	v_lshl_add_u64 v[196:197], v[158:159], 0, v[236:237]
	v_lshl_add_u64 v[212:213], v[158:159], 0, v[238:239]
	v_lshl_add_u64 v[158:159], v[158:159], 0, v[240:241]
	global_load_dwordx4 v[184:187], v[196:197], off
	global_load_dwordx4 v[188:191], v[196:197], off offset:64
	global_load_dwordx4 v[192:195], v[196:197], off offset:512
	s_nop 0
	global_load_dwordx4 v[196:199], v[196:197], off offset:576
	s_nop 0
	global_load_dwordx4 v[200:203], v[212:213], off
	global_load_dwordx4 v[204:207], v[212:213], off offset:64
	global_load_dwordx4 v[208:211], v[212:213], off offset:512
	s_nop 0
	global_load_dwordx4 v[212:215], v[212:213], off offset:576
	s_nop 0
	global_load_dwordx4 v[216:219], v[158:159], off
	global_load_dwordx4 v[220:223], v[158:159], off offset:64
	global_load_dwordx4 v[224:227], v[158:159], off offset:512
	global_load_dwordx4 v[228:231], v[158:159], off offset:576
	v_lshl_add_u64 v[158:159], s[6:7], 0, v[234:235]
	v_lshl_add_u64 v[158:159], v[158:159], 0, v[246:247]
	v_lshl_add_u64 v[234:235], s[6:7], 0, v[236:237]
	v_lshl_add_u64 v[236:237], s[6:7], 0, v[238:239]
	v_lshl_add_u64 v[238:239], s[6:7], 0, v[240:241]
	v_lshl_add_u64 v[234:235], v[234:235], 0, v[246:247]
	v_lshl_add_u64 v[236:237], v[236:237], 0, v[246:247]
	s_waitcnt vmcnt(0)
	v_pk_fma_f32 v[126:127], v[126:127], v[142:143], v[170:171]
	v_pk_fma_f32 v[124:125], v[124:125], v[140:141], v[168:169]
	v_pk_fma_f32 v[122:123], v[122:123], v[138:139], v[174:175]
	v_pk_fma_f32 v[120:121], v[120:121], v[136:137], v[172:173]
	v_pk_fma_f32 v[106:107], v[106:107], v[134:135], v[178:179]
	v_pk_fma_f32 v[104:105], v[104:105], v[132:133], v[176:177]
	v_pk_fma_f32 v[98:99], v[98:99], v[130:131], v[182:183]
	v_pk_fma_f32 v[96:97], v[96:97], v[128:129], v[180:181]
	s_nop 1
	v_mov_b32_e32 v252, v124
	v_mov_b32_e32 v253, v125
	v_mov_b32_e32 v254, v126
	v_mov_b32_e32 v255, v127
	v_mov_b32_dpp v124, v120 row_shr:8 row_mask:0xf bank_mask:0xc
	v_mov_b32_dpp v125, v121 row_shr:8 row_mask:0xf bank_mask:0xc
	v_mov_b32_dpp v126, v122 row_shr:8 row_mask:0xf bank_mask:0xc
	v_mov_b32_dpp v127, v123 row_shr:8 row_mask:0xf bank_mask:0xc
	v_mov_b32_dpp v120, v252 row_shl:8 row_mask:0xf bank_mask:0x3
	v_mov_b32_dpp v121, v253 row_shl:8 row_mask:0xf bank_mask:0x3
	v_mov_b32_dpp v122, v254 row_shl:8 row_mask:0xf bank_mask:0x3
	v_mov_b32_dpp v123, v255 row_shl:8 row_mask:0xf bank_mask:0x3
	v_lshl_add_u64 v[250:251], v[158:159], 0, v[248:249]
	global_store_dwordx4 v[158:159], v[124:127], off nt
	global_store_dwordx4 v[250:251], v[120:123], off nt
	s_nop 1
	v_mov_b32_e32 v252, v104
	v_mov_b32_e32 v253, v105
	v_mov_b32_e32 v254, v106
	v_mov_b32_e32 v255, v107
	v_mov_b32_dpp v104, v96 row_shr:8 row_mask:0xf bank_mask:0xc
	v_mov_b32_dpp v105, v97 row_shr:8 row_mask:0xf bank_mask:0xc
	v_mov_b32_dpp v106, v98 row_shr:8 row_mask:0xf bank_mask:0xc
	v_mov_b32_dpp v107, v99 row_shr:8 row_mask:0xf bank_mask:0xc
	v_mov_b32_dpp v96, v252 row_shl:8 row_mask:0xf bank_mask:0x3
	v_mov_b32_dpp v97, v253 row_shl:8 row_mask:0xf bank_mask:0x3
	v_mov_b32_dpp v98, v254 row_shl:8 row_mask:0xf bank_mask:0x3
	v_mov_b32_dpp v99, v255 row_shl:8 row_mask:0xf bank_mask:0x3
	v_lshl_add_u64 v[250:251], v[158:159], 0, v[248:249]
	global_store_dwordx4 v[158:159], v[104:107], off offset:512 nt
	global_store_dwordx4 v[250:251], v[96:99], off offset:512 nt
	v_lshl_add_u64 v[124:125], v[160:161], 0, s[20:21]
	v_lshl_add_u64 v[170:171], v[158:159], 0, s[16:17]
	v_pk_fma_f32 v[98:99], v[118:119], v[142:143], v[186:187]
	v_pk_fma_f32 v[96:97], v[116:117], v[140:141], v[184:185]
	v_pk_fma_f32 v[106:107], v[114:115], v[138:139], v[190:191]
	v_pk_fma_f32 v[80:81], v[80:81], v[132:133], v[208:209]
	v_pk_fma_f32 v[104:105], v[112:113], v[136:137], v[188:189]
	v_pk_fma_f32 v[90:91], v[90:91], v[134:135], v[194:195]
	v_pk_fma_f32 v[88:89], v[88:89], v[132:133], v[192:193]
	v_pk_fma_f32 v[86:87], v[86:87], v[130:131], v[198:199]
	v_pk_fma_f32 v[84:85], v[84:85], v[128:129], v[196:197]
	v_pk_fma_f32 v[110:111], v[110:111], v[142:143], v[202:203]
	v_pk_fma_f32 v[108:109], v[108:109], v[140:141], v[200:201]
	v_pk_fma_f32 v[102:103], v[102:103], v[138:139], v[206:207]
	v_pk_fma_f32 v[100:101], v[100:101], v[136:137], v[204:205]
;     __device__ __forceinline__ void operator()(const f32x4 (&acc)[2][2][4][2], const Unit& u, int wr, int wc, int fr, int fq) const {
;     ...
;             for (int m = 0; m < 4; ++m) { const size_t off = (row0 + ai * HALF + m * 16) * 1024 + col0;
; #pragma unroll
;                 for (int bj = 0; bj < 2; ++bj)
; #pragma unroll
;                     for (int n = 0; n < 2; ++n) xv[m][bj][n] = *(const f32x4*)(x + off + bj * HALF + n * 16); }
;             asm volatile("" ::: "memory");
; #pragma unroll
;             for (int m = 0; m < 4; ++m) { const size_t off = (row0 + ai * HALF + m * 16) * 1024 + col0;
; #pragma unroll
;                 for (int bj = 0; bj < 2; ++bj)
; #pragma unroll
;                     for (int n = 0; n < 2; ++n) *(f32x4*)(out + off + bj * HALF + n * 16) = xv[m][bj][n] + gv[bj][n] * acc[ai][bj][m][n]; }
	v_pk_fma_f32 v[82:83], v[82:83], v[134:135], v[210:211]
	v_pk_fma_f32 v[74:75], v[74:75], v[130:131], v[214:215]
	v_pk_fma_f32 v[72:73], v[72:73], v[128:129], v[212:213]
	s_nop 1
	v_mov_b32_e32 v252, v96
	v_mov_b32_e32 v253, v97
	v_mov_b32_e32 v254, v98
	v_mov_b32_e32 v255, v99
	v_mov_b32_dpp v96, v104 row_shr:8 row_mask:0xf bank_mask:0xc
	v_mov_b32_dpp v97, v105 row_shr:8 row_mask:0xf bank_mask:0xc
	v_mov_b32_dpp v98, v106 row_shr:8 row_mask:0xf bank_mask:0xc
	v_mov_b32_dpp v99, v107 row_shr:8 row_mask:0xf bank_mask:0xc
	v_mov_b32_dpp v104, v252 row_shl:8 row_mask:0xf bank_mask:0x3
	v_mov_b32_dpp v105, v253 row_shl:8 row_mask:0xf bank_mask:0x3
	v_mov_b32_dpp v106, v254 row_shl:8 row_mask:0xf bank_mask:0x3
	v_mov_b32_dpp v107, v255 row_shl:8 row_mask:0xf bank_mask:0x3
	v_lshl_add_u64 v[250:251], v[234:235], 0, v[248:249]
	global_store_dwordx4 v[234:235], v[96:99], off nt
	global_store_dwordx4 v[250:251], v[104:107], off nt
	s_nop 1
	v_mov_b32_e32 v252, v88
	v_mov_b32_e32 v253, v89
	v_mov_b32_e32 v254, v90
	v_mov_b32_e32 v255, v91
	v_mov_b32_dpp v88, v84 row_shr:8 row_mask:0xf bank_mask:0xc
	v_mov_b32_dpp v89, v85 row_shr:8 row_mask:0xf bank_mask:0xc
	v_mov_b32_dpp v90, v86 row_shr:8 row_mask:0xf bank_mask:0xc
	v_mov_b32_dpp v91, v87 row_shr:8 row_mask:0xf bank_mask:0xc
	v_mov_b32_dpp v84, v252 row_shl:8 row_mask:0xf bank_mask:0x3
	v_mov_b32_dpp v85, v253 row_shl:8 row_mask:0xf bank_mask:0x3
	v_mov_b32_dpp v86, v254 row_shl:8 row_mask:0xf bank_mask:0x3
	v_mov_b32_dpp v87, v255 row_shl:8 row_mask:0xf bank_mask:0x3
	v_lshl_add_u64 v[250:251], v[234:235], 0, v[248:249]
	global_store_dwordx4 v[234:235], v[88:91], off offset:512 nt
	global_store_dwordx4 v[250:251], v[84:87], off offset:512 nt
	s_nop 1
	v_mov_b32_e32 v252, v108
	v_mov_b32_e32 v253, v109
	v_mov_b32_e32 v254, v110
	v_mov_b32_e32 v255, v111
	v_mov_b32_dpp v108, v100 row_shr:8 row_mask:0xf bank_mask:0xc
	v_mov_b32_dpp v109, v101 row_shr:8 row_mask:0xf bank_mask:0xc
	v_mov_b32_dpp v110, v102 row_shr:8 row_mask:0xf bank_mask:0xc
	v_mov_b32_dpp v111, v103 row_shr:8 row_mask:0xf bank_mask:0xc
	v_mov_b32_dpp v100, v252 row_shl:8 row_mask:0xf bank_mask:0x3
	v_mov_b32_dpp v101, v253 row_shl:8 row_mask:0xf bank_mask:0x3
	v_mov_b32_dpp v102, v254 row_shl:8 row_mask:0xf bank_mask:0x3
	v_mov_b32_dpp v103, v255 row_shl:8 row_mask:0xf bank_mask:0x3
	v_lshl_add_u64 v[250:251], v[236:237], 0, v[248:249]
	global_store_dwordx4 v[236:237], v[108:111], off nt
	global_store_dwordx4 v[250:251], v[100:103], off nt
	s_nop 1
	v_mov_b32_e32 v252, v80
	v_mov_b32_e32 v253, v81
	v_mov_b32_e32 v254, v82
	v_mov_b32_e32 v255, v83
	v_mov_b32_dpp v80, v72 row_shr:8 row_mask:0xf bank_mask:0xc
	v_mov_b32_dpp v81, v73 row_shr:8 row_mask:0xf bank_mask:0xc
	v_mov_b32_dpp v82, v74 row_shr:8 row_mask:0xf bank_mask:0xc
	v_mov_b32_dpp v83, v75 row_shr:8 row_mask:0xf bank_mask:0xc
	v_mov_b32_dpp v72, v252 row_shl:8 row_mask:0xf bank_mask:0x3
	v_mov_b32_dpp v73, v253 row_shl:8 row_mask:0xf bank_mask:0x3
	v_mov_b32_dpp v74, v254 row_shl:8 row_mask:0xf bank_mask:0x3
	v_mov_b32_dpp v75, v255 row_shl:8 row_mask:0xf bank_mask:0x3
	v_lshl_add_u64 v[250:251], v[236:237], 0, v[248:249]
	global_store_dwordx4 v[236:237], v[80:83], off offset:512 nt
	global_store_dwordx4 v[250:251], v[72:75], off offset:512 nt
	v_pk_fma_f32 v[66:67], v[66:67], v[130:131], v[230:231]
	v_lshl_add_u64 v[80:81], v[238:239], 0, v[246:247]
	v_pk_fma_f32 v[64:65], v[64:65], v[128:129], v[228:229]
	v_pk_fma_f32 v[94:95], v[94:95], v[142:143], v[218:219]
	v_pk_fma_f32 v[92:93], v[92:93], v[140:141], v[216:217]
	v_add_co_u32_e32 v242, vcc, s57, v160
	v_pk_fma_f32 v[74:75], v[78:79], v[138:139], v[222:223]
	v_pk_fma_f32 v[72:73], v[76:77], v[136:137], v[220:221]
	v_pk_fma_f32 v[70:71], v[70:71], v[134:135], v[226:227]
	v_pk_fma_f32 v[68:69], v[68:69], v[132:133], v[224:225]
	v_addc_co_u32_e32 v243, vcc, 0, v161, vcc
	s_nop 1
	v_mov_b32_e32 v252, v92
	v_mov_b32_e32 v253, v93
	v_mov_b32_e32 v254, v94
	v_mov_b32_e32 v255, v95
	v_mov_b32_dpp v92, v72 row_shr:8 row_mask:0xf bank_mask:0xc
	v_mov_b32_dpp v93, v73 row_shr:8 row_mask:0xf bank_mask:0xc
	v_mov_b32_dpp v94, v74 row_shr:8 row_mask:0xf bank_mask:0xc
	v_mov_b32_dpp v95, v75 row_shr:8 row_mask:0xf bank_mask:0xc
	v_mov_b32_dpp v72, v252 row_shl:8 row_mask:0xf bank_mask:0x3
	v_mov_b32_dpp v73, v253 row_shl:8 row_mask:0xf bank_mask:0x3
	v_mov_b32_dpp v74, v254 row_shl:8 row_mask:0xf bank_mask:0x3
	v_mov_b32_dpp v75, v255 row_shl:8 row_mask:0xf bank_mask:0x3
	v_lshl_add_u64 v[250:251], v[80:81], 0, v[248:249]
	global_store_dwordx4 v[80:81], v[92:95], off nt
	global_store_dwordx4 v[250:251], v[72:75], off nt
	s_nop 1
	v_mov_b32_e32 v252, v68
	v_mov_b32_e32 v253, v69
	v_mov_b32_e32 v254, v70
	v_mov_b32_e32 v255, v71
	v_mov_b32_dpp v68, v64 row_shr:8 row_mask:0xf bank_mask:0xc
	v_mov_b32_dpp v69, v65 row_shr:8 row_mask:0xf bank_mask:0xc
	v_mov_b32_dpp v70, v66 row_shr:8 row_mask:0xf bank_mask:0xc
	v_mov_b32_dpp v71, v67 row_shr:8 row_mask:0xf bank_mask:0xc
	v_mov_b32_dpp v64, v252 row_shl:8 row_mask:0xf bank_mask:0x3
	v_mov_b32_dpp v65, v253 row_shl:8 row_mask:0xf bank_mask:0x3
	v_mov_b32_dpp v66, v254 row_shl:8 row_mask:0xf bank_mask:0x3
	v_mov_b32_dpp v67, v255 row_shl:8 row_mask:0xf bank_mask:0x3
	v_lshl_add_u64 v[250:251], v[80:81], 0, v[248:249]
	global_store_dwordx4 v[80:81], v[68:71], off offset:512 nt
	global_store_dwordx4 v[250:251], v[64:67], off offset:512 nt
	v_add_co_u32_e32 v80, vcc, s58, v160
	v_lshl_add_u64 v[76:77], v[160:161], 0, s[14:15]
	s_nop 0
	v_addc_co_u32_e32 v81, vcc, 0, v161, vcc
	v_lshl_add_u64 v[92:93], v[160:161], 0, s[16:17]
	v_add_co_u32_e32 v96, vcc, s59, v160
	global_load_dwordx4 v[64:67], v[242:243], off
	s_nop 0
	global_load_dwordx4 v[68:71], v[76:77], off offset:64
	global_load_dwordx4 v[72:75], v[76:77], off offset:512
	s_nop 0
	global_load_dwordx4 v[76:79], v[76:77], off offset:576
	v_addc_co_u32_e32 v97, vcc, 0, v161, vcc
	global_load_dwordx4 v[80:83], v[80:81], off
	s_nop 0
	global_load_dwordx4 v[84:87], v[92:93], off offset:64
	global_load_dwordx4 v[88:91], v[92:93], off offset:512
	s_nop 0
	global_load_dwordx4 v[92:95], v[92:93], off offset:576
	v_lshl_add_u64 v[108:109], v[160:161], 0, s[18:19]
	global_load_dwordx4 v[96:99], v[96:97], off
	v_add_co_u32_e32 v112, vcc, s60, v160
	global_load_dwordx4 v[100:103], v[108:109], off offset:64
	global_load_dwordx4 v[104:107], v[108:109], off offset:512
	s_nop 0
	global_load_dwordx4 v[108:111], v[108:109], off offset:576
	v_addc_co_u32_e32 v113, vcc, 0, v161, vcc
	global_load_dwordx4 v[112:115], v[112:113], off
	s_nop 0
	global_load_dwordx4 v[116:119], v[124:125], off offset:64
	global_load_dwordx4 v[120:123], v[124:125], off offset:512
	s_nop 0
	global_load_dwordx4 v[124:127], v[124:125], off offset:576
	v_lshl_add_u64 v[160:161], v[158:159], 0, s[14:15]
	s_nop 0
	s_waitcnt vmcnt(15)
;     __device__ __forceinline__ void operator()(const f32x4 (&acc)[2][2][4][2], const Unit& u, int wr, int wc, int fr, int fq) const {
;     ...
;             for (int m = 0; m < 4; ++m) { const size_t off = (row0 + ai * HALF + m * 16) * 1024 + col0;
; #pragma unroll
;                 for (int bj = 0; bj < 2; ++bj)
; #pragma unroll
;                     for (int n = 0; n < 2; ++n) *(f32x4*)(out + off + bj * HALF + n * 16) = xv[m][bj][n] + gv[bj][n] * acc[ai][bj][m][n]; }
	v_pk_fma_f32 v[62:63], v[62:63], v[142:143], v[66:67]
	v_pk_fma_f32 v[60:61], v[60:61], v[140:141], v[64:65]
	s_waitcnt vmcnt(14)
	v_pk_fma_f32 v[58:59], v[58:59], v[138:139], v[70:71]
	v_pk_fma_f32 v[56:57], v[56:57], v[136:137], v[68:69]
	s_waitcnt vmcnt(13)
	v_pk_fma_f32 v[46:47], v[46:47], v[134:135], v[74:75]
	s_waitcnt vmcnt(8)
	v_pk_fma_f32 v[30:31], v[30:31], v[130:131], v[94:95]
	v_pk_fma_f32 v[44:45], v[44:45], v[132:133], v[72:73]
	v_pk_fma_f32 v[42:43], v[42:43], v[130:131], v[78:79]
	v_pk_fma_f32 v[40:41], v[40:41], v[128:129], v[76:77]
	v_pk_fma_f32 v[54:55], v[54:55], v[142:143], v[82:83]
	v_pk_fma_f32 v[52:53], v[52:53], v[140:141], v[80:81]
	v_pk_fma_f32 v[50:51], v[50:51], v[138:139], v[86:87]
	v_pk_fma_f32 v[48:49], v[48:49], v[136:137], v[84:85]
	v_pk_fma_f32 v[38:39], v[38:39], v[134:135], v[90:91]
	v_pk_fma_f32 v[36:37], v[36:37], v[132:133], v[88:89]
	v_pk_fma_f32 v[28:29], v[28:29], v[128:129], v[92:93]
	s_nop 1
	v_mov_b32_e32 v252, v60
	v_mov_b32_e32 v253, v61
	v_mov_b32_e32 v254, v62
	v_mov_b32_e32 v255, v63
	v_mov_b32_dpp v60, v56 row_shr:8 row_mask:0xf bank_mask:0xc
	v_mov_b32_dpp v61, v57 row_shr:8 row_mask:0xf bank_mask:0xc
	v_mov_b32_dpp v62, v58 row_shr:8 row_mask:0xf bank_mask:0xc
	v_mov_b32_dpp v63, v59 row_shr:8 row_mask:0xf bank_mask:0xc
	v_mov_b32_dpp v56, v252 row_shl:8 row_mask:0xf bank_mask:0x3
	v_mov_b32_dpp v57, v253 row_shl:8 row_mask:0xf bank_mask:0x3
	v_mov_b32_dpp v58, v254 row_shl:8 row_mask:0xf bank_mask:0x3
	v_mov_b32_dpp v59, v255 row_shl:8 row_mask:0xf bank_mask:0x3
	v_lshl_add_u64 v[250:251], v[160:161], 0, v[248:249]
	global_store_dwordx4 v[160:161], v[60:63], off nt
	global_store_dwordx4 v[250:251], v[56:59], off nt
	s_nop 1
	v_mov_b32_e32 v252, v44
	v_mov_b32_e32 v253, v45
	v_mov_b32_e32 v254, v46
	v_mov_b32_e32 v255, v47
	v_mov_b32_dpp v44, v40 row_shr:8 row_mask:0xf bank_mask:0xc
	v_mov_b32_dpp v45, v41 row_shr:8 row_mask:0xf bank_mask:0xc
	v_mov_b32_dpp v46, v42 row_shr:8 row_mask:0xf bank_mask:0xc
	v_mov_b32_dpp v47, v43 row_shr:8 row_mask:0xf bank_mask:0xc
	v_mov_b32_dpp v40, v252 row_shl:8 row_mask:0xf bank_mask:0x3
	v_mov_b32_dpp v41, v253 row_shl:8 row_mask:0xf bank_mask:0x3
	v_mov_b32_dpp v42, v254 row_shl:8 row_mask:0xf bank_mask:0x3
	v_mov_b32_dpp v43, v255 row_shl:8 row_mask:0xf bank_mask:0x3
	v_lshl_add_u64 v[250:251], v[160:161], 0, v[248:249]
	global_store_dwordx4 v[160:161], v[44:47], off offset:512 nt
	global_store_dwordx4 v[250:251], v[40:43], off offset:512 nt
	s_nop 1
	v_mov_b32_e32 v252, v52
	v_mov_b32_e32 v253, v53
	v_mov_b32_e32 v254, v54
	v_mov_b32_e32 v255, v55
	v_mov_b32_dpp v52, v48 row_shr:8 row_mask:0xf bank_mask:0xc
	v_mov_b32_dpp v53, v49 row_shr:8 row_mask:0xf bank_mask:0xc
	v_mov_b32_dpp v54, v50 row_shr:8 row_mask:0xf bank_mask:0xc
	v_mov_b32_dpp v55, v51 row_shr:8 row_mask:0xf bank_mask:0xc
	v_mov_b32_dpp v48, v252 row_shl:8 row_mask:0xf bank_mask:0x3
	v_mov_b32_dpp v49, v253 row_shl:8 row_mask:0xf bank_mask:0x3
	v_mov_b32_dpp v50, v254 row_shl:8 row_mask:0xf bank_mask:0x3
	v_mov_b32_dpp v51, v255 row_shl:8 row_mask:0xf bank_mask:0x3
	v_lshl_add_u64 v[250:251], v[170:171], 0, v[248:249]
	global_store_dwordx4 v[170:171], v[52:55], off nt
	global_store_dwordx4 v[250:251], v[48:51], off nt
	s_nop 1
	v_mov_b32_e32 v252, v36
	v_mov_b32_e32 v253, v37
	v_mov_b32_e32 v254, v38
	v_mov_b32_e32 v255, v39
	v_mov_b32_dpp v36, v28 row_shr:8 row_mask:0xf bank_mask:0xc
	v_mov_b32_dpp v37, v29 row_shr:8 row_mask:0xf bank_mask:0xc
	v_mov_b32_dpp v38, v30 row_shr:8 row_mask:0xf bank_mask:0xc
	v_mov_b32_dpp v39, v31 row_shr:8 row_mask:0xf bank_mask:0xc
	v_mov_b32_dpp v28, v252 row_shl:8 row_mask:0xf bank_mask:0x3
	v_mov_b32_dpp v29, v253 row_shl:8 row_mask:0xf bank_mask:0x3
	v_mov_b32_dpp v30, v254 row_shl:8 row_mask:0xf bank_mask:0x3
	v_mov_b32_dpp v31, v255 row_shl:8 row_mask:0xf bank_mask:0x3
	v_lshl_add_u64 v[250:251], v[170:171], 0, v[248:249]
	global_store_dwordx4 v[170:171], v[36:39], off offset:512 nt
	global_store_dwordx4 v[250:251], v[28:31], off offset:512 nt
	s_waitcnt vmcnt(13)
; #define PG8_BAR __builtin_amdgcn_s_barrier()
;     __device__ __forceinline__ void operator()(const f32x4 (&acc)[2][2][4][2], const Unit& u, int wr, int wc, int fr, int fq) const {
;     ...
;             for (int m = 0; m < 4; ++m) { const size_t off = (row0 + ai * HALF + m * 16) * 1024 + col0;
; #pragma unroll
;                 for (int bj = 0; bj < 2; ++bj)
; #pragma unroll
;                     for (int n = 0; n < 2; ++n) *(f32x4*)(out + off + bj * HALF + n * 16) = xv[m][bj][n] + gv[bj][n] * acc[ai][bj][m][n]; }
;             asm volatile("" ::: "memory"); }
; template <class Epi, class Sched, bool ALIGN_EPI = false, bool SP2 = false>
; __device__ __forceinline__ void gemm_phase(PG8_LAS unsigned char* lds, const Gemm g, const Sched& S, const Epi& E) {
;     ...
;         if (!has_next) break;
; #pragma unroll
;         for (int a = 0; a < 2; ++a)
; #pragma unroll
;             for (int b = 0; b < 2; ++b)
; #pragma unroll
;                 for (int m = 0; m < 4; ++m)
; #pragma unroll
;                     for (int n = 0; n < 2; ++n) acc[a][b][m][n] = (f32x4){0.f, 0.f, 0.f, 0.f};
;         cur = nxt; cA = nA; cB = nB; ++ui;
;         if constexpr (ALIGN_EPI) { if (wr == 1) PG8_BAR; }
;     }
	v_pk_fma_f32 v[18:19], v[18:19], v[134:135], v[106:107]
	v_pk_fma_f32 v[16:17], v[16:17], v[132:133], v[104:105]
	v_pk_fma_f32 v[30:31], v[34:35], v[142:143], v[98:99]
	v_pk_fma_f32 v[28:29], v[32:33], v[140:141], v[96:97]
	v_lshl_add_u64 v[32:33], v[158:159], 0, s[18:19]
	s_waitcnt vmcnt(12)
	v_pk_fma_f32 v[14:15], v[14:15], v[130:131], v[110:111]
	v_pk_fma_f32 v[12:13], v[12:13], v[128:129], v[108:109]
	v_pk_fma_f32 v[26:27], v[26:27], v[138:139], v[102:103]
	v_pk_fma_f32 v[24:25], v[24:25], v[136:137], v[100:101]
	s_nop 1
	v_mov_b32_e32 v252, v16
	v_mov_b32_e32 v253, v17
	v_mov_b32_e32 v254, v18
	v_mov_b32_e32 v255, v19
	v_mov_b32_dpp v16, v12 row_shr:8 row_mask:0xf bank_mask:0xc
	v_mov_b32_dpp v17, v13 row_shr:8 row_mask:0xf bank_mask:0xc
	v_mov_b32_dpp v18, v14 row_shr:8 row_mask:0xf bank_mask:0xc
	v_mov_b32_dpp v19, v15 row_shr:8 row_mask:0xf bank_mask:0xc
	v_mov_b32_dpp v12, v252 row_shl:8 row_mask:0xf bank_mask:0x3
	v_mov_b32_dpp v13, v253 row_shl:8 row_mask:0xf bank_mask:0x3
	v_mov_b32_dpp v14, v254 row_shl:8 row_mask:0xf bank_mask:0x3
	v_mov_b32_dpp v15, v255 row_shl:8 row_mask:0xf bank_mask:0x3
	v_lshl_add_u64 v[250:251], v[32:33], 0, v[248:249]
	global_store_dwordx4 v[32:33], v[16:19], off offset:512 nt
	global_store_dwordx4 v[250:251], v[12:15], off offset:512 nt
	v_lshl_add_u64 v[244:245], v[158:159], 0, s[20:21]
	s_waitcnt vmcnt(13)
	v_pk_fma_f32 v[14:15], v[22:23], v[142:143], v[114:115]
	v_pk_fma_f32 v[12:13], v[20:21], v[140:141], v[112:113]
	s_waitcnt vmcnt(12)
	v_pk_fma_f32 v[10:11], v[10:11], v[138:139], v[118:119]
	v_pk_fma_f32 v[8:9], v[8:9], v[136:137], v[116:117]
	s_waitcnt vmcnt(11)
	v_pk_fma_f32 v[6:7], v[6:7], v[134:135], v[122:123]
	v_pk_fma_f32 v[4:5], v[4:5], v[132:133], v[120:121]
	s_waitcnt vmcnt(10)
	v_pk_fma_f32 v[2:3], v[2:3], v[130:131], v[126:127]
	v_pk_fma_f32 v[0:1], v[0:1], v[128:129], v[124:125]
	s_nop 1
	v_mov_b32_e32 v252, v28
	v_mov_b32_e32 v253, v29
	v_mov_b32_e32 v254, v30
	v_mov_b32_e32 v255, v31
	v_mov_b32_dpp v28, v24 row_shr:8 row_mask:0xf bank_mask:0xc
	v_mov_b32_dpp v29, v25 row_shr:8 row_mask:0xf bank_mask:0xc
	v_mov_b32_dpp v30, v26 row_shr:8 row_mask:0xf bank_mask:0xc
	v_mov_b32_dpp v31, v27 row_shr:8 row_mask:0xf bank_mask:0xc
	v_mov_b32_dpp v24, v252 row_shl:8 row_mask:0xf bank_mask:0x3
	v_mov_b32_dpp v25, v253 row_shl:8 row_mask:0xf bank_mask:0x3
	v_mov_b32_dpp v26, v254 row_shl:8 row_mask:0xf bank_mask:0x3
	v_mov_b32_dpp v27, v255 row_shl:8 row_mask:0xf bank_mask:0x3
	v_lshl_add_u64 v[250:251], v[32:33], 0, v[248:249]
	global_store_dwordx4 v[32:33], v[28:31], off nt
	global_store_dwordx4 v[250:251], v[24:27], off nt
	s_nop 1
	v_mov_b32_e32 v252, v12
	v_mov_b32_e32 v253, v13
	v_mov_b32_e32 v254, v14
	v_mov_b32_e32 v255, v15
	v_mov_b32_dpp v12, v8 row_shr:8 row_mask:0xf bank_mask:0xc
	v_mov_b32_dpp v13, v9 row_shr:8 row_mask:0xf bank_mask:0xc
	v_mov_b32_dpp v14, v10 row_shr:8 row_mask:0xf bank_mask:0xc
	v_mov_b32_dpp v15, v11 row_shr:8 row_mask:0xf bank_mask:0xc
	v_mov_b32_dpp v8, v252 row_shl:8 row_mask:0xf bank_mask:0x3
	v_mov_b32_dpp v9, v253 row_shl:8 row_mask:0xf bank_mask:0x3
	v_mov_b32_dpp v10, v254 row_shl:8 row_mask:0xf bank_mask:0x3
	v_mov_b32_dpp v11, v255 row_shl:8 row_mask:0xf bank_mask:0x3
	v_lshl_add_u64 v[250:251], v[244:245], 0, v[248:249]
	global_store_dwordx4 v[244:245], v[12:15], off nt
	global_store_dwordx4 v[250:251], v[8:11], off nt
	s_nop 1
	v_mov_b32_e32 v252, v4
	v_mov_b32_e32 v253, v5
	v_mov_b32_e32 v254, v6
	v_mov_b32_e32 v255, v7
	v_mov_b32_dpp v4, v0 row_shr:8 row_mask:0xf bank_mask:0xc
	v_mov_b32_dpp v5, v1 row_shr:8 row_mask:0xf bank_mask:0xc
	v_mov_b32_dpp v6, v2 row_shr:8 row_mask:0xf bank_mask:0xc
	v_mov_b32_dpp v7, v3 row_shr:8 row_mask:0xf bank_mask:0xc
	v_mov_b32_dpp v0, v252 row_shl:8 row_mask:0xf bank_mask:0x3
	v_mov_b32_dpp v1, v253 row_shl:8 row_mask:0xf bank_mask:0x3
	v_mov_b32_dpp v2, v254 row_shl:8 row_mask:0xf bank_mask:0x3
	v_mov_b32_dpp v3, v255 row_shl:8 row_mask:0xf bank_mask:0x3
	v_lshl_add_u64 v[250:251], v[244:245], 0, v[248:249]
	global_store_dwordx4 v[244:245], v[4:7], off offset:512 nt
	global_store_dwordx4 v[250:251], v[0:3], off offset:512 nt
	s_andn2_b64 vcc, exec, s[0:1]
	s_mov_b64 s[0:1], -1
	s_cbranch_vccnz .LBB0_577
	s_andn2_b64 vcc, exec, s[8:9]
	s_cbranch_vccnz .LBB0_576
	s_barrier
	s_branch .LBB0_576
